# EpiRes epilogues (down/out proj): residual loads of rows 5-7 prefetched right after the first batch into free registers, removing the second exposed load+store-drain wait
# baseline (speedup 1.0000x reference)
; #define GAS __attribute__((address_space(1)))
; __device__ __forceinline__ float sigmoidf_fast(float z) { return fast_rcp(1.f + fast_exp2(-z * LOG2E)); }
; __device__ __forceinline__ float bf_lo(unsigned w) { return __uint_as_float(w << 16); }
;   __device__ __forceinline__ void operator()(ACC_T, const Unit& u, int wr, int wc, int fr, int fq) const {
;     ...
;     for (int b0 = 0; b0 < 16; b0 += NB) {
;       u32x4 hq[NB], pq[GATED ? NB : 1];
; #pragma unroll
;       for (int k = 0; k < NB; ++k) {
;         const int st = b0 + k, ri = st >> 1;
;         const size_t off = (size_t)erow(u, ri >> 2, wr, ri & 3, fr) * DM + cbase + 128 * (st & 1);
;         hq[k] = *(GAS const u32x4*)(hres + off);
;         if (GATED) pq[k] = *(GAS const u32x4*)(projb + off);
;       }
; #pragma unroll
;       for (int k = 0; k < NB; ++k) {
;         const int st = b0 + k, ri = st >> 1, bj = st & 1, ai = ri >> 2, m = ri & 3;
;         const int row = erow(u, ai, wr, m, fr);
;         const u32x4 hnx = hq[k];
;         f32x4 h0, h1;
;         h0[0] = bf_lo(hnx.x); h0[1] = bf_hi(hnx.x); h0[2] = bf_lo(hnx.y); h0[3] = bf_hi(hnx.y);
;         h1[0] = bf_lo(hnx.z); h1[1] = bf_hi(hnx.z); h1[2] = bf_lo(hnx.w); h1[3] = bf_hi(hnx.w);
;         const float rg = GATED ? rs[ai][m] : 0.f;
;         const size_t off = (size_t)row * DM + cbase + 128 * bj;
;         float pr[8];
;         if (GATED) {
;           const u32x4 pw = pq[k];
;           pr[0] = bf_lo(pw.x); pr[1] = bf_hi(pw.x); pr[2] = bf_lo(pw.y); pr[3] = bf_hi(pw.y);
;           pr[4] = bf_lo(pw.z); pr[5] = bf_hi(pw.z); pr[6] = bf_lo(pw.w); pr[7] = bf_hi(pw.w);
;         }
;         f32x4 v0, v1;
; #pragma unroll
;         for (int j = 0; j < 4; ++j) {
;           const float a0 = acc[ai][bj][m][0][j], a1 = acc[ai][bj][m][1][j];
;           const float d0 = GATED ? sigmoidf_fast(a0 * rg) * pr[j] : scale * a0;
;           const float d1 = GATED ? sigmoidf_fast(a1 * rg) * pr[4 + j] : scale * a1;
;           v0[j] = h0[j] + d0; v1[j] = h1[j] + d1;
;           ss += v0[j] * v0[j] + v1[j] * v1[j];
;         }
;         *(GAS u32x4*)(hb + off) = pack8(v0, v1, 1.f);
;         if (bj == 1) {
;           ss += __shfl_xor(ss, 16); ss += __shfl_xor(ss, 32);
;           if (fq == 0) ((GAS float*)ssq_out)[(size_t)row * 16 + 4 * u.pn + wc] = ss;
;           ss = 0.f;
;         }
.LBB0_374:
	v_lshl_or_b32 v182, s20, 8, v202
	v_lshl_add_u32 v186, s28, 8, v200
	v_ashrrev_i32_e32 v183, 31, v182
	v_lshlrev_b64 v[214:215], 1, v[182:183]
	v_ashrrev_i32_e32 v187, 31, v186
	v_lshl_add_u64 v[184:185], v[2:3], 0, v[214:215]
	v_lshlrev_b64 v[216:217], 11, v[186:187]
	v_lshl_add_u64 v[132:133], v[184:185], 0, v[216:217]
	global_load_dwordx4 v[206:209], v[132:133], off
	global_load_dwordx4 v[210:213], v[132:133], off offset:256
	v_or_b32_e32 v196, 16, v186
	v_or_b32_e32 v192, 32, v186
	v_or_b32_e32 v188, 48, v186
	v_ashrrev_i32_e32 v197, 31, v196
	v_ashrrev_i32_e32 v193, 31, v192
	v_ashrrev_i32_e32 v189, 31, v188
	v_lshlrev_b64 v[198:199], 11, v[196:197]
	v_lshlrev_b64 v[194:195], 11, v[192:193]
	v_lshlrev_b64 v[190:191], 11, v[188:189]
	v_lshl_add_u64 v[132:133], v[184:185], 0, v[198:199]
	v_lshl_add_u64 v[134:135], v[184:185], 0, v[194:195]
	v_lshl_add_u64 v[218:219], v[184:185], 0, v[190:191]
	global_load_dwordx4 v[152:155], v[132:133], off
	global_load_dwordx4 v[148:151], v[132:133], off offset:256
	global_load_dwordx4 v[144:147], v[134:135], off
	global_load_dwordx4 v[140:143], v[134:135], off offset:256
	global_load_dwordx4 v[136:139], v[218:219], off
	s_nop 0
	global_load_dwordx4 v[132:135], v[218:219], off offset:256
	v_add_u32_e32 v226, 0x80, v186
	v_ashrrev_i32_e32 v227, 31, v226
	v_lshlrev_b64 v[226:227], 11, v[226:227]
	v_lshl_add_u64 v[252:253], v[184:185], 0, v[226:227]
	global_load_dwordx4 v[228:231], v[252:253], off
	global_load_dwordx4 v[232:235], v[252:253], off offset:256
	v_add_u32_e32 v226, 0x90, v186
	v_ashrrev_i32_e32 v227, 31, v226
	v_lshlrev_b64 v[226:227], 11, v[226:227]
	v_lshl_add_u64 v[252:253], v[184:185], 0, v[226:227]
	global_load_dwordx4 v[236:239], v[252:253], off
	global_load_dwordx4 v[240:243], v[252:253], off offset:256
	v_add_u32_e32 v226, 0xa0, v186
	v_ashrrev_i32_e32 v227, 31, v226
	v_lshlrev_b64 v[226:227], 11, v[226:227]
	v_lshl_add_u64 v[252:253], v[184:185], 0, v[226:227]
	global_load_dwordx4 v[244:247], v[252:253], off
	global_load_dwordx4 v[248:251], v[252:253], off offset:256
	v_and_b32_e32 v218, 64, v204
	v_xor_b32_e32 v205, 16, v204
	v_add_u32_e32 v218, 64, v218
	v_xor_b32_e32 v219, 32, v204
	v_cmp_lt_i32_e32 vcc, v205, v218
	v_lshl_add_u64 v[216:217], v[0:1], 0, v[216:217]
	v_lshl_add_u64 v[214:215], v[216:217], 0, v[214:215]
	v_cndmask_b32_e32 v205, v204, v205, vcc
	v_cmp_lt_i32_e32 vcc, v219, v218
	v_lshlrev_b32_e32 v205, 2, v205
	s_lshl_b32 s12, s20, 2
	v_cndmask_b32_e32 v224, v204, v219, vcc
	s_ashr_i32 s13, s12, 31
	s_waitcnt vmcnt(6)
	v_lshlrev_b32_e32 v218, 16, v208
	v_and_b32_e32 v219, 0xffff0000, v208
	v_lshlrev_b32_e32 v216, 16, v206
	v_and_b32_e32 v217, 0xffff0000, v206
	v_lshlrev_b32_e32 v208, 16, v209
	v_and_b32_e32 v209, 0xffff0000, v209
	v_lshlrev_b32_e32 v222, 16, v212
	v_and_b32_e32 v223, 0xffff0000, v212
	v_lshlrev_b32_e32 v212, 16, v213
	v_and_b32_e32 v213, 0xffff0000, v213
	v_pk_fma_f32 v[128:129], v[128:129], 0.5, v[218:219] op_sel_hi:[1,0,1]
	v_lshlrev_b32_e32 v206, 16, v207
	v_and_b32_e32 v207, 0xffff0000, v207
	v_lshlrev_b32_e32 v220, 16, v210
	v_and_b32_e32 v221, 0xffff0000, v210
	v_lshlrev_b32_e32 v210, 16, v211
	v_and_b32_e32 v211, 0xffff0000, v211
	v_pk_fma_f32 v[124:125], v[124:125], 0.5, v[216:217] op_sel_hi:[1,0,1]
	v_pk_fma_f32 v[130:131], v[130:131], 0.5, v[208:209] op_sel_hi:[1,0,1]
	v_pk_fma_f32 v[208:209], v[118:119], 0.5, v[212:213] op_sel_hi:[1,0,1]
	v_pk_mul_f32 v[118:119], v[128:129], v[128:129]
	v_pk_fma_f32 v[126:127], v[126:127], 0.5, v[206:207] op_sel_hi:[1,0,1]
	v_pk_fma_f32 v[122:123], v[122:123], 0.5, v[210:211] op_sel_hi:[1,0,1]
	v_pk_mul_f32 v[210:211], v[130:131], v[130:131]
	v_pk_fma_f32 v[118:119], v[124:125], v[124:125], v[118:119]
	v_pk_fma_f32 v[206:207], v[116:117], 0.5, v[222:223] op_sel_hi:[1,0,1]
	v_cvt_pk_bf16_f32 v116, v124, v125
	v_pk_fma_f32 v[124:125], v[126:127], v[126:127], v[210:211]
	v_add_f32_e32 v118, v118, v119
	v_pk_fma_f32 v[120:121], v[120:121], 0.5, v[220:221] op_sel_hi:[1,0,1]
	v_pk_mul_f32 v[212:213], v[206:207], v[206:207]
	v_add_f32_e32 v118, v124, v118
	v_cvt_pk_bf16_f32 v117, v126, v127
	v_pk_fma_f32 v[126:127], v[120:121], v[120:121], v[212:213]
	v_add_f32_e32 v118, v125, v118
	v_pk_mul_f32 v[216:217], v[208:209], v[208:209]
	v_add_f32_e32 v118, v126, v118
	v_pk_fma_f32 v[210:211], v[122:123], v[122:123], v[216:217]
	v_add_f32_e32 v118, v127, v118
	v_add_f32_e32 v118, v210, v118
	v_add_f32_e32 v124, v211, v118
	ds_bpermute_b32 v125, v205, v124
	v_cvt_pk_bf16_f32 v118, v128, v129
	v_cvt_pk_bf16_f32 v119, v130, v131
	global_store_dwordx4 v[214:215], v[116:119], off
	v_cvt_pk_bf16_f32 v120, v120, v121
	v_cvt_pk_bf16_f32 v121, v122, v123
	s_waitcnt lgkmcnt(0)
	v_add_f32_e32 v117, v124, v125
	v_lshlrev_b32_e32 v116, 2, v224
	ds_bpermute_b32 v118, v116, v117
	v_cvt_pk_bf16_f32 v122, v206, v207
	v_cvt_pk_bf16_f32 v123, v208, v209
	global_store_dwordx4 v[214:215], v[120:123], off offset:256
	s_and_saveexec_b64 s[28:29], s[6:7]
	s_cbranch_execz .LBB0_376
	s_waitcnt lgkmcnt(0)
	v_add_f32_e32 v117, v117, v118
	v_lshlrev_b64 v[118:119], 6, v[186:187]
	v_lshl_add_u64 v[118:119], v[160:161], 0, v[118:119]
	v_lshl_add_u64 v[118:119], s[12:13], 2, v[118:119]
	s_lshl_b32 s20, s46, 2
	v_lshl_add_u64 v[118:119], v[118:119], 0, s[20:21]
	global_store_dword v[118:119], v117, off

; #define GAS __attribute__((address_space(1)))
; __device__ __forceinline__ float sigmoidf_fast(float z) { return fast_rcp(1.f + fast_exp2(-z * LOG2E)); }
; __device__ __forceinline__ float bf_lo(unsigned w) { return __uint_as_float(w << 16); }
; __device__ __forceinline__ float bf_hi(unsigned w) { return __uint_as_float(w & 0xffff0000u); }
;   __device__ __forceinline__ void operator()(ACC_T, const Unit& u, int wr, int wc, int fr, int fq) const {
;     ...
; #pragma unroll
;       for (int k = 0; k < NB; ++k) {
;         const int st = b0 + k, ri = st >> 1;
;         const size_t off = (size_t)erow(u, ri >> 2, wr, ri & 3, fr) * DM + cbase + 128 * (st & 1);
;         hq[k] = *(GAS const u32x4*)(hres + off);
;         if (GATED) pq[k] = *(GAS const u32x4*)(projb + off);
;       }
; #pragma unroll
;       for (int k = 0; k < NB; ++k) {
;         const int st = b0 + k, ri = st >> 1, bj = st & 1, ai = ri >> 2, m = ri & 3;
;         const int row = erow(u, ai, wr, m, fr);
;         const u32x4 hnx = hq[k];
;         f32x4 h0, h1;
;         h0[0] = bf_lo(hnx.x); h0[1] = bf_hi(hnx.x); h0[2] = bf_lo(hnx.y); h0[3] = bf_hi(hnx.y);
;         h1[0] = bf_lo(hnx.z); h1[1] = bf_hi(hnx.z); h1[2] = bf_lo(hnx.w); h1[3] = bf_hi(hnx.w);
;         const float rg = GATED ? rs[ai][m] : 0.f;
;         const size_t off = (size_t)row * DM + cbase + 128 * bj;
;         float pr[8];
;         if (GATED) {
;           const u32x4 pw = pq[k];
;           pr[0] = bf_lo(pw.x); pr[1] = bf_hi(pw.x); pr[2] = bf_lo(pw.y); pr[3] = bf_hi(pw.y);
;           pr[4] = bf_lo(pw.z); pr[5] = bf_hi(pw.z); pr[6] = bf_lo(pw.w); pr[7] = bf_hi(pw.w);
;         }
;         f32x4 v0, v1;
; #pragma unroll
;         for (int j = 0; j < 4; ++j) {
;           const float a0 = acc[ai][bj][m][0][j], a1 = acc[ai][bj][m][1][j];
;           const float d0 = GATED ? sigmoidf_fast(a0 * rg) * pr[j] : scale * a0;
;           const float d1 = GATED ? sigmoidf_fast(a1 * rg) * pr[4 + j] : scale * a1;
;           v0[j] = h0[j] + d0; v1[j] = h1[j] + d1;
;           ss += v0[j] * v0[j] + v1[j] * v1[j];
;         }
;         *(GAS u32x4*)(hb + off) = pack8(v0, v1, 1.f);
;         if (bj == 1) {
;           ss += __shfl_xor(ss, 16); ss += __shfl_xor(ss, 32);
;           if (fq == 0) ((GAS float*)ssq_out)[(size_t)row * 16 + 4 * u.pn + wc] = ss;
;           ss = 0.f;
;         }
.LBB0_382:
	s_or_b64 exec, exec, s[28:29]
	v_add_u32_e32 v100, 0x80, v186
	v_ashrrev_i32_e32 v101, 31, v100
	v_lshlrev_b64 v[110:111], 11, v[100:101]
	s_waitcnt lgkmcnt(0)
	v_lshl_add_u64 v[68:69], v[184:185], 0, v[110:111]
	s_waitcnt vmcnt(8)
	v_mov_b32_e32 v102, v228
	v_mov_b32_e32 v103, v229
	v_mov_b32_e32 v104, v230
	v_mov_b32_e32 v105, v231
	v_mov_b32_e32 v106, v232
	v_mov_b32_e32 v107, v233
	v_mov_b32_e32 v108, v234
	v_mov_b32_e32 v109, v235
	v_add_u32_e32 v96, 0x90, v186
	v_add_u32_e32 v94, 0xa0, v186
	v_add_u32_e32 v92, 0xb0, v186
	v_ashrrev_i32_e32 v97, 31, v96
	v_ashrrev_i32_e32 v95, 31, v94
	v_ashrrev_i32_e32 v93, 31, v92
	v_lshlrev_b64 v[98:99], 11, v[96:97]
	v_lshlrev_b64 v[68:69], 11, v[94:95]
	v_lshlrev_b64 v[70:71], 11, v[92:93]
	v_lshl_add_u64 v[72:73], v[184:185], 0, v[98:99]
	v_lshl_add_u64 v[68:69], v[184:185], 0, v[68:69]
	v_lshl_add_u64 v[70:71], v[184:185], 0, v[70:71]
	v_mov_b32_e32 v88, v236
	v_mov_b32_e32 v89, v237
	v_mov_b32_e32 v90, v238
	v_mov_b32_e32 v91, v239
	v_mov_b32_e32 v84, v240
	v_mov_b32_e32 v85, v241
	v_mov_b32_e32 v86, v242
	v_mov_b32_e32 v87, v243
	v_mov_b32_e32 v80, v244
	v_mov_b32_e32 v81, v245
	v_mov_b32_e32 v82, v246
	v_mov_b32_e32 v83, v247
	v_mov_b32_e32 v76, v248
	v_mov_b32_e32 v77, v249
	v_mov_b32_e32 v78, v250
	v_mov_b32_e32 v79, v251
	s_nop 0
	global_load_dwordx4 v[72:75], v[70:71], off
	s_nop 0
	global_load_dwordx4 v[68:71], v[70:71], off offset:256
	v_lshlrev_b32_e32 v114, 16, v104
	v_and_b32_e32 v115, 0xffff0000, v104
	v_lshlrev_b32_e32 v112, 16, v102
	v_and_b32_e32 v113, 0xffff0000, v102
	v_lshlrev_b32_e32 v104, 16, v105
	v_and_b32_e32 v105, 0xffff0000, v105
	v_lshlrev_b32_e32 v120, 16, v108
	v_and_b32_e32 v121, 0xffff0000, v108
	v_lshlrev_b32_e32 v108, 16, v109
	v_and_b32_e32 v109, 0xffff0000, v109
	v_pk_fma_f32 v[60:61], v[60:61], 0.5, v[114:115] op_sel_hi:[1,0,1]
	v_lshlrev_b32_e32 v102, 16, v103
	v_and_b32_e32 v103, 0xffff0000, v103
	v_pk_fma_f32 v[64:65], v[64:65], 0.5, v[112:113] op_sel_hi:[1,0,1]
	v_pk_fma_f32 v[62:63], v[62:63], 0.5, v[104:105] op_sel_hi:[1,0,1]
	v_pk_fma_f32 v[104:105], v[54:55], 0.5, v[108:109] op_sel_hi:[1,0,1]
	v_cvt_pk_bf16_f32 v54, v60, v61
	v_pk_mul_f32 v[60:61], v[60:61], v[60:61]
	v_pk_fma_f32 v[66:67], v[66:67], 0.5, v[102:103] op_sel_hi:[1,0,1]
	v_cvt_pk_bf16_f32 v55, v62, v63
	v_pk_mul_f32 v[62:63], v[62:63], v[62:63]
	v_pk_fma_f32 v[60:61], v[64:65], v[64:65], v[60:61]
	v_lshlrev_b32_e32 v118, 16, v106
	v_and_b32_e32 v119, 0xffff0000, v106
	v_lshlrev_b32_e32 v106, 16, v107
	v_and_b32_e32 v107, 0xffff0000, v107
	v_pk_fma_f32 v[102:103], v[52:53], 0.5, v[120:121] op_sel_hi:[1,0,1]
	v_pk_fma_f32 v[62:63], v[66:67], v[66:67], v[62:63]
	v_add_f32_e32 v60, v60, v61
	v_pk_fma_f32 v[56:57], v[56:57], 0.5, v[118:119] op_sel_hi:[1,0,1]
	v_pk_fma_f32 v[58:59], v[58:59], 0.5, v[106:107] op_sel_hi:[1,0,1]
	v_pk_mul_f32 v[106:107], v[102:103], v[102:103]
	v_add_f32_e32 v60, v62, v60
	v_cvt_pk_bf16_f32 v52, v64, v65
	v_pk_fma_f32 v[64:65], v[56:57], v[56:57], v[106:107]
	v_add_f32_e32 v60, v63, v60
	v_pk_mul_f32 v[108:109], v[104:105], v[104:105]
	v_add_f32_e32 v60, v64, v60
	v_cvt_pk_bf16_f32 v53, v66, v67
	v_pk_fma_f32 v[66:67], v[58:59], v[58:59], v[108:109]
	v_add_f32_e32 v60, v65, v60
	v_add_f32_e32 v60, v66, v60
	v_add_f32_e32 v62, v67, v60
	ds_bpermute_b32 v63, v205, v62
	v_lshl_add_u64 v[60:61], v[0:1], 0, v[110:111]
	v_lshl_add_u64 v[60:61], v[182:183], 1, v[60:61]
	global_store_dwordx4 v[60:61], v[52:55], off
	s_waitcnt lgkmcnt(0)
	s_nop 0
	v_add_f32_e32 v52, v62, v63
	ds_bpermute_b32 v53, v116, v52
	v_cvt_pk_bf16_f32 v54, v56, v57
	v_cvt_pk_bf16_f32 v55, v58, v59
	v_cvt_pk_bf16_f32 v56, v102, v103
	v_cvt_pk_bf16_f32 v57, v104, v105
	global_store_dwordx4 v[60:61], v[54:57], off offset:256
	s_and_saveexec_b64 s[28:29], s[6:7]
	s_cbranch_execz .LBB0_384
	s_waitcnt lgkmcnt(0)
	v_add_f32_e32 v54, v52, v53
	v_lshlrev_b64 v[52:53], 6, v[100:101]
	v_lshl_add_u64 v[52:53], v[160:161], 0, v[52:53]
	v_lshl_add_u64 v[52:53], s[12:13], 2, v[52:53]
	s_lshl_b32 s20, s46, 2
	v_lshl_add_u64 v[52:53], v[52:53], 0, s[20:21]
	global_store_dword v[52:53], v54, off
; #define GAS __attribute__((address_space(1)))
; __device__ __forceinline__ float sigmoidf_fast(float z) { return fast_rcp(1.f + fast_exp2(-z * LOG2E)); }
; __device__ __forceinline__ float bf_lo(unsigned w) { return __uint_as_float(w << 16); }
; __device__ __forceinline__ float bf_hi(unsigned w) { return __uint_as_float(w & 0xffff0000u); }
;   __device__ __forceinline__ void operator()(ACC_T, const Unit& u, int wr, int wc, int fr, int fq) const {
;     ...
; #pragma unroll
;       for (int k = 0; k < NB; ++k) {
;         const int st = b0 + k, ri = st >> 1, bj = st & 1, ai = ri >> 2, m = ri & 3;
;         const int row = erow(u, ai, wr, m, fr);
;         const u32x4 hnx = hq[k];
;         f32x4 h0, h1;
;         h0[0] = bf_lo(hnx.x); h0[1] = bf_hi(hnx.x); h0[2] = bf_lo(hnx.y); h0[3] = bf_hi(hnx.y);
;         h1[0] = bf_lo(hnx.z); h1[1] = bf_hi(hnx.z); h1[2] = bf_lo(hnx.w); h1[3] = bf_hi(hnx.w);
;         const float rg = GATED ? rs[ai][m] : 0.f;
;         const size_t off = (size_t)row * DM + cbase + 128 * bj;
;         float pr[8];
;         if (GATED) {
;           const u32x4 pw = pq[k];
;           pr[0] = bf_lo(pw.x); pr[1] = bf_hi(pw.x); pr[2] = bf_lo(pw.y); pr[3] = bf_hi(pw.y);
;           pr[4] = bf_lo(pw.z); pr[5] = bf_hi(pw.z); pr[6] = bf_lo(pw.w); pr[7] = bf_hi(pw.w);
;         }
;         f32x4 v0, v1;
; #pragma unroll
;         for (int j = 0; j < 4; ++j) {
;           const float a0 = acc[ai][bj][m][0][j], a1 = acc[ai][bj][m][1][j];
;           const float d0 = GATED ? sigmoidf_fast(a0 * rg) * pr[j] : scale * a0;
;           const float d1 = GATED ? sigmoidf_fast(a1 * rg) * pr[4 + j] : scale * a1;
;           v0[j] = h0[j] + d0; v1[j] = h1[j] + d1;
;           ss += v0[j] * v0[j] + v1[j] * v1[j];
;         }
;         *(GAS u32x4*)(hb + off) = pack8(v0, v1, 1.f);
;         if (bj == 1) {
;           ss += __shfl_xor(ss, 16); ss += __shfl_xor(ss, 32);
;           if (fq == 0) ((GAS float*)ssq_out)[(size_t)row * 16 + 4 * u.pn + wc] = ss;
;           ss = 0.f;
;         }
.LBB0_384:
	s_or_b64 exec, exec, s[28:29]
	v_lshlrev_b32_e32 v52, 16, v88
	s_waitcnt lgkmcnt(0)
	v_and_b32_e32 v53, 0xffff0000, v88
	v_lshlrev_b32_e32 v56, 16, v84
	v_and_b32_e32 v57, 0xffff0000, v84
	v_pk_fma_f32 v[48:49], v[48:49], 0.5, v[52:53] op_sel_hi:[1,0,1]
	v_lshlrev_b32_e32 v52, 16, v90
	v_and_b32_e32 v53, 0xffff0000, v90
	v_pk_fma_f32 v[40:41], v[40:41], 0.5, v[56:57] op_sel_hi:[1,0,1]
	v_lshlrev_b32_e32 v56, 16, v86
	v_and_b32_e32 v57, 0xffff0000, v86
	v_pk_fma_f32 v[52:53], v[44:45], 0.5, v[52:53] op_sel_hi:[1,0,1]
	v_lshlrev_b32_e32 v44, 16, v89
	v_and_b32_e32 v45, 0xffff0000, v89
	v_pk_fma_f32 v[56:57], v[36:37], 0.5, v[56:57] op_sel_hi:[1,0,1]
	v_lshlrev_b32_e32 v36, 16, v85
	v_and_b32_e32 v37, 0xffff0000, v85
	v_pk_fma_f32 v[50:51], v[50:51], 0.5, v[44:45] op_sel_hi:[1,0,1]
	v_lshlrev_b32_e32 v44, 16, v91
	v_and_b32_e32 v45, 0xffff0000, v91
	v_pk_fma_f32 v[42:43], v[42:43], 0.5, v[36:37] op_sel_hi:[1,0,1]
	v_lshlrev_b32_e32 v36, 16, v87
	v_and_b32_e32 v37, 0xffff0000, v87
	v_pk_fma_f32 v[54:55], v[46:47], 0.5, v[44:45] op_sel_hi:[1,0,1]
	v_pk_fma_f32 v[58:59], v[38:39], 0.5, v[36:37] op_sel_hi:[1,0,1]
	v_pk_mul_f32 v[36:37], v[52:53], v[52:53]
	v_pk_mul_f32 v[38:39], v[54:55], v[54:55]
	v_pk_fma_f32 v[36:37], v[48:49], v[48:49], v[36:37]
	v_pk_fma_f32 v[38:39], v[50:51], v[50:51], v[38:39]
	v_add_f32_e32 v36, v36, v37
	v_cvt_pk_bf16_f32 v44, v48, v49
	v_pk_mul_f32 v[48:49], v[56:57], v[56:57]
	v_add_f32_e32 v36, v38, v36
	v_pk_fma_f32 v[48:49], v[40:41], v[40:41], v[48:49]
	v_add_f32_e32 v36, v39, v36
	v_cvt_pk_bf16_f32 v45, v50, v51
	v_pk_mul_f32 v[50:51], v[58:59], v[58:59]
	v_add_f32_e32 v36, v48, v36
	v_pk_fma_f32 v[50:51], v[42:43], v[42:43], v[50:51]
	v_add_f32_e32 v36, v49, v36
	v_add_f32_e32 v36, v50, v36
	v_add_f32_e32 v39, v51, v36
	ds_bpermute_b32 v50, v205, v39
	v_lshl_add_u64 v[36:37], v[0:1], 0, v[98:99]
	v_lshl_add_u64 v[48:49], v[182:183], 1, v[36:37]
	v_cvt_pk_bf16_f32 v46, v52, v53
	v_cvt_pk_bf16_f32 v47, v54, v55
	s_waitcnt lgkmcnt(0)
	v_add_f32_e32 v36, v39, v50
	ds_bpermute_b32 v37, v116, v36
	v_cvt_pk_bf16_f32 v38, v40, v41
	v_cvt_pk_bf16_f32 v39, v42, v43
	v_cvt_pk_bf16_f32 v40, v56, v57
	v_cvt_pk_bf16_f32 v41, v58, v59
	global_store_dwordx4 v[48:49], v[44:47], off
	global_store_dwordx4 v[48:49], v[38:41], off offset:256
	s_and_saveexec_b64 s[28:29], s[6:7]
	s_cbranch_execz .LBB0_386
	s_waitcnt lgkmcnt(0)
	v_add_f32_e32 v38, v36, v37
	v_lshlrev_b64 v[36:37], 6, v[96:97]
	v_lshl_add_u64 v[36:37], v[160:161], 0, v[36:37]
	v_lshl_add_u64 v[36:37], s[12:13], 2, v[36:37]
	s_lshl_b32 s20, s46, 2
	v_lshl_add_u64 v[36:37], v[36:37], 0, s[20:21]
	global_store_dword v[36:37], v38, off
.LBB0_386:
	s_or_b64 exec, exec, s[28:29]
	v_lshlrev_b32_e32 v36, 16, v80
	s_waitcnt lgkmcnt(0)
	v_and_b32_e32 v37, 0xffff0000, v80
	v_lshlrev_b32_e32 v42, 16, v76
	v_and_b32_e32 v43, 0xffff0000, v76
	v_pk_fma_f32 v[32:33], v[32:33], 0.5, v[36:37] op_sel_hi:[1,0,1]
	v_lshlrev_b32_e32 v36, 16, v82
	v_and_b32_e32 v37, 0xffff0000, v82
	v_pk_fma_f32 v[24:25], v[24:25], 0.5, v[42:43] op_sel_hi:[1,0,1]
	v_lshlrev_b32_e32 v42, 16, v78
	v_and_b32_e32 v43, 0xffff0000, v78
	v_pk_fma_f32 v[36:37], v[28:29], 0.5, v[36:37] op_sel_hi:[1,0,1]
	v_lshlrev_b32_e32 v28, 16, v81
	v_and_b32_e32 v29, 0xffff0000, v81
	v_pk_fma_f32 v[42:43], v[20:21], 0.5, v[42:43] op_sel_hi:[1,0,1]
	v_lshlrev_b32_e32 v20, 16, v77
	v_and_b32_e32 v21, 0xffff0000, v77
	v_pk_fma_f32 v[34:35], v[34:35], 0.5, v[28:29] op_sel_hi:[1,0,1]
	v_lshlrev_b32_e32 v28, 16, v83
	v_and_b32_e32 v29, 0xffff0000, v83
	v_pk_fma_f32 v[26:27], v[26:27], 0.5, v[20:21] op_sel_hi:[1,0,1]
	v_lshlrev_b32_e32 v20, 16, v79
	v_and_b32_e32 v21, 0xffff0000, v79
	v_pk_fma_f32 v[38:39], v[30:31], 0.5, v[28:29] op_sel_hi:[1,0,1]
	v_pk_fma_f32 v[44:45], v[22:23], 0.5, v[20:21] op_sel_hi:[1,0,1]
	v_pk_mul_f32 v[20:21], v[36:37], v[36:37]
	v_pk_mul_f32 v[22:23], v[38:39], v[38:39]
	v_pk_fma_f32 v[20:21], v[32:33], v[32:33], v[20:21]
	v_pk_fma_f32 v[22:23], v[34:35], v[34:35], v[22:23]
	v_add_f32_e32 v20, v20, v21
	v_cvt_pk_bf16_f32 v28, v32, v33
	v_pk_mul_f32 v[32:33], v[42:43], v[42:43]
	v_add_f32_e32 v20, v22, v20
	v_pk_fma_f32 v[32:33], v[24:25], v[24:25], v[32:33]
	v_add_f32_e32 v20, v23, v20
	v_cvt_pk_bf16_f32 v29, v34, v35
	v_pk_mul_f32 v[34:35], v[44:45], v[44:45]
	v_add_f32_e32 v20, v32, v20
	v_pk_fma_f32 v[34:35], v[26:27], v[26:27], v[34:35]
	v_add_f32_e32 v20, v33, v20
	v_add_f32_e32 v20, v34, v20
	v_add_f32_e32 v23, v35, v20
	ds_bpermute_b32 v34, v205, v23
	v_lshlrev_b64 v[40:41], 11, v[94:95]
	v_lshl_add_u64 v[20:21], v[0:1], 0, v[40:41]
	v_lshl_add_u64 v[32:33], v[182:183], 1, v[20:21]
	v_cvt_pk_bf16_f32 v30, v36, v37
	s_waitcnt lgkmcnt(0)
	v_add_f32_e32 v20, v23, v34
	ds_bpermute_b32 v21, v116, v20
	v_cvt_pk_bf16_f32 v31, v38, v39
	v_cvt_pk_bf16_f32 v22, v24, v25
	v_cvt_pk_bf16_f32 v23, v26, v27
	v_cvt_pk_bf16_f32 v24, v42, v43
	v_cvt_pk_bf16_f32 v25, v44, v45
	global_store_dwordx4 v[32:33], v[28:31], off
	global_store_dwordx4 v[32:33], v[22:25], off offset:256
	s_and_saveexec_b64 s[28:29], s[6:7]
	s_cbranch_execz .LBB0_388
	s_waitcnt lgkmcnt(0)
	v_add_f32_e32 v22, v20, v21
	v_lshlrev_b64 v[20:21], 6, v[94:95]
	v_lshl_add_u64 v[20:21], v[160:161], 0, v[20:21]
	v_lshl_add_u64 v[20:21], s[12:13], 2, v[20:21]
	s_lshl_b32 s20, s46, 2
	v_lshl_add_u64 v[20:21], v[20:21], 0, s[20:21]
	global_store_dword v[20:21], v22, off

; #define GAS __attribute__((address_space(1)))
; __device__ __forceinline__ float sigmoidf_fast(float z) { return fast_rcp(1.f + fast_exp2(-z * LOG2E)); }
; __device__ __forceinline__ float bf_lo(unsigned w) { return __uint_as_float(w << 16); }
;   __device__ __forceinline__ void operator()(ACC_T, const Unit& u, int wr, int wc, int fr, int fq) const {
;     ...
;     for (int b0 = 0; b0 < 16; b0 += NB) {
;       u32x4 hq[NB], pq[GATED ? NB : 1];
; #pragma unroll
;       for (int k = 0; k < NB; ++k) {
;         const int st = b0 + k, ri = st >> 1;
;         const size_t off = (size_t)erow(u, ri >> 2, wr, ri & 3, fr) * DM + cbase + 128 * (st & 1);
;         hq[k] = *(GAS const u32x4*)(hres + off);
;         if (GATED) pq[k] = *(GAS const u32x4*)(projb + off);
;       }
; #pragma unroll
;       for (int k = 0; k < NB; ++k) {
;         const int st = b0 + k, ri = st >> 1, bj = st & 1, ai = ri >> 2, m = ri & 3;
;         const int row = erow(u, ai, wr, m, fr);
;         const u32x4 hnx = hq[k];
;         f32x4 h0, h1;
;         h0[0] = bf_lo(hnx.x); h0[1] = bf_hi(hnx.x); h0[2] = bf_lo(hnx.y); h0[3] = bf_hi(hnx.y);
;         h1[0] = bf_lo(hnx.z); h1[1] = bf_hi(hnx.z); h1[2] = bf_lo(hnx.w); h1[3] = bf_hi(hnx.w);
;         const float rg = GATED ? rs[ai][m] : 0.f;
;         const size_t off = (size_t)row * DM + cbase + 128 * bj;
;         float pr[8];
;         if (GATED) {
;           const u32x4 pw = pq[k];
;           pr[0] = bf_lo(pw.x); pr[1] = bf_hi(pw.x); pr[2] = bf_lo(pw.y); pr[3] = bf_hi(pw.y);
;           pr[4] = bf_lo(pw.z); pr[5] = bf_hi(pw.z); pr[6] = bf_lo(pw.w); pr[7] = bf_hi(pw.w);
;         }
;         f32x4 v0, v1;
; #pragma unroll
;         for (int j = 0; j < 4; ++j) {
;           const float a0 = acc[ai][bj][m][0][j], a1 = acc[ai][bj][m][1][j];
;           const float d0 = GATED ? sigmoidf_fast(a0 * rg) * pr[j] : scale * a0;
;           const float d1 = GATED ? sigmoidf_fast(a1 * rg) * pr[4 + j] : scale * a1;
;           v0[j] = h0[j] + d0; v1[j] = h1[j] + d1;
;           ss += v0[j] * v0[j] + v1[j] * v1[j];
;         }
;         *(GAS u32x4*)(hb + off) = pack8(v0, v1, 1.f);
;         if (bj == 1) {
;           ss += __shfl_xor(ss, 16); ss += __shfl_xor(ss, 32);
;           if (fq == 0) ((GAS float*)ssq_out)[(size_t)row * 16 + 4 * u.pn + wc] = ss;
;           ss = 0.f;
;         }
.LBB0_943:
	v_lshl_or_b32 v180, s20, 8, v200
	v_lshl_add_u32 v184, s28, 8, v198
	v_ashrrev_i32_e32 v181, 31, v180
	v_lshlrev_b64 v[214:215], 1, v[180:181]
	v_ashrrev_i32_e32 v185, 31, v184
	v_lshl_add_u64 v[182:183], v[152:153], 0, v[214:215]
	v_lshlrev_b64 v[204:205], 11, v[184:185]
	v_lshl_add_u64 v[128:129], v[182:183], 0, v[204:205]
	global_load_dwordx4 v[206:209], v[128:129], off
	global_load_dwordx4 v[210:213], v[128:129], off offset:256
	v_or_b32_e32 v194, 16, v184
	v_or_b32_e32 v190, 32, v184
	v_or_b32_e32 v186, 48, v184
	v_ashrrev_i32_e32 v195, 31, v194
	v_ashrrev_i32_e32 v191, 31, v190
	v_ashrrev_i32_e32 v187, 31, v186
	v_lshlrev_b64 v[196:197], 11, v[194:195]
	v_lshlrev_b64 v[192:193], 11, v[190:191]
	v_lshlrev_b64 v[188:189], 11, v[186:187]
	v_lshl_add_u64 v[128:129], v[182:183], 0, v[196:197]
	v_lshl_add_u64 v[130:131], v[182:183], 0, v[192:193]
	v_lshl_add_u64 v[216:217], v[182:183], 0, v[188:189]
	global_load_dwordx4 v[148:151], v[128:129], off
	global_load_dwordx4 v[144:147], v[128:129], off offset:256
	global_load_dwordx4 v[140:143], v[130:131], off
	global_load_dwordx4 v[136:139], v[130:131], off offset:256
	global_load_dwordx4 v[132:135], v[216:217], off
	s_nop 0
	global_load_dwordx4 v[128:131], v[216:217], off offset:256
	v_add_u32_e32 v226, 0x80, v184
	v_ashrrev_i32_e32 v227, 31, v226
	v_lshlrev_b64 v[226:227], 11, v[226:227]
	v_lshl_add_u64 v[252:253], v[182:183], 0, v[226:227]
	global_load_dwordx4 v[228:231], v[252:253], off
	global_load_dwordx4 v[232:235], v[252:253], off offset:256
	v_add_u32_e32 v226, 0x90, v184
	v_ashrrev_i32_e32 v227, 31, v226
	v_lshlrev_b64 v[226:227], 11, v[226:227]
	v_lshl_add_u64 v[252:253], v[182:183], 0, v[226:227]
	global_load_dwordx4 v[236:239], v[252:253], off
	global_load_dwordx4 v[240:243], v[252:253], off offset:256
	v_add_u32_e32 v226, 0xa0, v184
	v_ashrrev_i32_e32 v227, 31, v226
	v_lshlrev_b64 v[226:227], 11, v[226:227]
	v_lshl_add_u64 v[252:253], v[182:183], 0, v[226:227]
	global_load_dwordx4 v[244:247], v[252:253], off
	global_load_dwordx4 v[248:251], v[252:253], off offset:256
	v_and_b32_e32 v217, 64, v203
	v_xor_b32_e32 v216, 16, v203
	v_add_u32_e32 v217, 64, v217
	v_xor_b32_e32 v218, 32, v203
	v_cmp_lt_i32_e32 vcc, v216, v217
	s_lshl_b32 s12, s20, 2
	s_ashr_i32 s13, s12, 31
	v_cndmask_b32_e32 v219, v203, v216, vcc
	v_cmp_lt_i32_e32 vcc, v218, v217
	v_lshl_add_u64 v[216:217], v[152:153], 0, v[204:205]
	v_lshlrev_b32_e32 v204, 2, v219
	v_cndmask_b32_e32 v224, v203, v218, vcc
	v_lshl_add_u64 v[214:215], v[216:217], 0, v[214:215]
	s_waitcnt vmcnt(6)
	v_lshlrev_b32_e32 v218, 16, v208
	v_and_b32_e32 v219, 0xffff0000, v208
	v_lshlrev_b32_e32 v216, 16, v206
	v_and_b32_e32 v217, 0xffff0000, v206
	v_lshlrev_b32_e32 v208, 16, v209
	v_and_b32_e32 v209, 0xffff0000, v209
	v_lshlrev_b32_e32 v222, 16, v212
	v_and_b32_e32 v223, 0xffff0000, v212
	v_lshlrev_b32_e32 v212, 16, v213
	v_and_b32_e32 v213, 0xffff0000, v213
	v_pk_add_f32 v[124:125], v[124:125], v[218:219]
	v_lshlrev_b32_e32 v206, 16, v207
	v_and_b32_e32 v207, 0xffff0000, v207
	v_lshlrev_b32_e32 v220, 16, v210
	v_and_b32_e32 v221, 0xffff0000, v210
	v_lshlrev_b32_e32 v210, 16, v211
	v_and_b32_e32 v211, 0xffff0000, v211
	v_pk_add_f32 v[120:121], v[120:121], v[216:217]
	v_pk_add_f32 v[126:127], v[126:127], v[208:209]
	v_pk_add_f32 v[208:209], v[114:115], v[212:213]
	v_pk_mul_f32 v[114:115], v[124:125], v[124:125]
	v_pk_add_f32 v[122:123], v[122:123], v[206:207]
	v_pk_add_f32 v[118:119], v[118:119], v[210:211]
	v_pk_mul_f32 v[210:211], v[126:127], v[126:127]
	v_pk_fma_f32 v[114:115], v[120:121], v[120:121], v[114:115]
	v_pk_add_f32 v[206:207], v[112:113], v[222:223]
	v_cvt_pk_bf16_f32 v112, v120, v121
	v_pk_fma_f32 v[120:121], v[122:123], v[122:123], v[210:211]
	v_add_f32_e32 v114, v114, v115
	v_pk_add_f32 v[116:117], v[116:117], v[220:221]
	v_pk_mul_f32 v[212:213], v[206:207], v[206:207]
	v_add_f32_e32 v114, v120, v114
	v_cvt_pk_bf16_f32 v113, v122, v123
	v_pk_fma_f32 v[122:123], v[116:117], v[116:117], v[212:213]
	v_add_f32_e32 v114, v121, v114
	v_pk_mul_f32 v[216:217], v[208:209], v[208:209]
	v_add_f32_e32 v114, v122, v114
	v_pk_fma_f32 v[210:211], v[118:119], v[118:119], v[216:217]
	v_add_f32_e32 v114, v123, v114
	v_add_f32_e32 v114, v210, v114
	v_add_f32_e32 v120, v211, v114
	ds_bpermute_b32 v121, v204, v120
	v_cvt_pk_bf16_f32 v114, v124, v125
	v_cvt_pk_bf16_f32 v115, v126, v127
	global_store_dwordx4 v[214:215], v[112:115], off
	v_cvt_pk_bf16_f32 v116, v116, v117
	v_cvt_pk_bf16_f32 v117, v118, v119
	s_waitcnt lgkmcnt(0)
	v_add_f32_e32 v113, v120, v121
	v_lshlrev_b32_e32 v112, 2, v224
	ds_bpermute_b32 v114, v112, v113
	v_cvt_pk_bf16_f32 v118, v206, v207
	v_cvt_pk_bf16_f32 v119, v208, v209
	global_store_dwordx4 v[214:215], v[116:119], off offset:256
	s_and_saveexec_b64 s[28:29], s[6:7]
	s_cbranch_execz .LBB0_945
	s_waitcnt lgkmcnt(0)
	v_add_f32_e32 v113, v113, v114
	v_lshlrev_b64 v[114:115], 6, v[184:185]
	v_lshl_add_u64 v[114:115], v[154:155], 0, v[114:115]
	v_lshl_add_u64 v[114:115], s[12:13], 2, v[114:115]
	s_lshl_b32 s20, s46, 2
	v_lshl_add_u64 v[114:115], v[114:115], 0, s[20:21]
	global_store_dword v[114:115], v113, off

; #define GAS __attribute__((address_space(1)))
; __device__ __forceinline__ float sigmoidf_fast(float z) { return fast_rcp(1.f + fast_exp2(-z * LOG2E)); }
; __device__ __forceinline__ float bf_lo(unsigned w) { return __uint_as_float(w << 16); }
; __device__ __forceinline__ float bf_hi(unsigned w) { return __uint_as_float(w & 0xffff0000u); }
;   __device__ __forceinline__ void operator()(ACC_T, const Unit& u, int wr, int wc, int fr, int fq) const {
;     ...
; #pragma unroll
;       for (int k = 0; k < NB; ++k) {
;         const int st = b0 + k, ri = st >> 1;
;         const size_t off = (size_t)erow(u, ri >> 2, wr, ri & 3, fr) * DM + cbase + 128 * (st & 1);
;         hq[k] = *(GAS const u32x4*)(hres + off);
;         if (GATED) pq[k] = *(GAS const u32x4*)(projb + off);
;       }
; #pragma unroll
;       for (int k = 0; k < NB; ++k) {
;         const int st = b0 + k, ri = st >> 1, bj = st & 1, ai = ri >> 2, m = ri & 3;
;         const int row = erow(u, ai, wr, m, fr);
;         const u32x4 hnx = hq[k];
;         f32x4 h0, h1;
;         h0[0] = bf_lo(hnx.x); h0[1] = bf_hi(hnx.x); h0[2] = bf_lo(hnx.y); h0[3] = bf_hi(hnx.y);
;         h1[0] = bf_lo(hnx.z); h1[1] = bf_hi(hnx.z); h1[2] = bf_lo(hnx.w); h1[3] = bf_hi(hnx.w);
;         const float rg = GATED ? rs[ai][m] : 0.f;
;         const size_t off = (size_t)row * DM + cbase + 128 * bj;
;         float pr[8];
;         if (GATED) {
;           const u32x4 pw = pq[k];
;           pr[0] = bf_lo(pw.x); pr[1] = bf_hi(pw.x); pr[2] = bf_lo(pw.y); pr[3] = bf_hi(pw.y);
;           pr[4] = bf_lo(pw.z); pr[5] = bf_hi(pw.z); pr[6] = bf_lo(pw.w); pr[7] = bf_hi(pw.w);
;         }
;         f32x4 v0, v1;
; #pragma unroll
;         for (int j = 0; j < 4; ++j) {
;           const float a0 = acc[ai][bj][m][0][j], a1 = acc[ai][bj][m][1][j];
;           const float d0 = GATED ? sigmoidf_fast(a0 * rg) * pr[j] : scale * a0;
;           const float d1 = GATED ? sigmoidf_fast(a1 * rg) * pr[4 + j] : scale * a1;
;           v0[j] = h0[j] + d0; v1[j] = h1[j] + d1;
;           ss += v0[j] * v0[j] + v1[j] * v1[j];
;         }
;         *(GAS u32x4*)(hb + off) = pack8(v0, v1, 1.f);
;         if (bj == 1) {
;           ss += __shfl_xor(ss, 16); ss += __shfl_xor(ss, 32);
;           if (fq == 0) ((GAS float*)ssq_out)[(size_t)row * 16 + 4 * u.pn + wc] = ss;
;           ss = 0.f;
;         }
.LBB0_951:
	s_or_b64 exec, exec, s[28:29]
	v_add_u32_e32 v96, 0x80, v184
	v_ashrrev_i32_e32 v97, 31, v96
	v_lshlrev_b64 v[106:107], 11, v[96:97]
	s_waitcnt lgkmcnt(0)
	v_lshl_add_u64 v[64:65], v[182:183], 0, v[106:107]
	s_waitcnt vmcnt(8)
	v_mov_b32_e32 v98, v228
	v_mov_b32_e32 v99, v229
	v_mov_b32_e32 v100, v230
	v_mov_b32_e32 v101, v231
	v_mov_b32_e32 v102, v232
	v_mov_b32_e32 v103, v233
	v_mov_b32_e32 v104, v234
	v_mov_b32_e32 v105, v235
	v_add_u32_e32 v92, 0x90, v184
	v_add_u32_e32 v90, 0xa0, v184
	v_add_u32_e32 v88, 0xb0, v184
	v_ashrrev_i32_e32 v93, 31, v92
	v_ashrrev_i32_e32 v91, 31, v90
	v_ashrrev_i32_e32 v89, 31, v88
	v_lshlrev_b64 v[94:95], 11, v[92:93]
	v_lshlrev_b64 v[64:65], 11, v[90:91]
	v_lshlrev_b64 v[66:67], 11, v[88:89]
	v_lshl_add_u64 v[68:69], v[182:183], 0, v[94:95]
	v_lshl_add_u64 v[64:65], v[182:183], 0, v[64:65]
	v_lshl_add_u64 v[66:67], v[182:183], 0, v[66:67]
	v_mov_b32_e32 v84, v236
	v_mov_b32_e32 v85, v237
	v_mov_b32_e32 v86, v238
	v_mov_b32_e32 v87, v239
	v_mov_b32_e32 v80, v240
	v_mov_b32_e32 v81, v241
	v_mov_b32_e32 v82, v242
	v_mov_b32_e32 v83, v243
	v_mov_b32_e32 v76, v244
	v_mov_b32_e32 v77, v245
	v_mov_b32_e32 v78, v246
	v_mov_b32_e32 v79, v247
	v_mov_b32_e32 v72, v248
	v_mov_b32_e32 v73, v249
	v_mov_b32_e32 v74, v250
	v_mov_b32_e32 v75, v251
	s_nop 0
	global_load_dwordx4 v[68:71], v[66:67], off
	s_nop 0
	global_load_dwordx4 v[64:67], v[66:67], off offset:256
	v_lshlrev_b32_e32 v110, 16, v100
	v_and_b32_e32 v111, 0xffff0000, v100
	v_lshlrev_b32_e32 v108, 16, v98
	v_and_b32_e32 v109, 0xffff0000, v98
	v_lshlrev_b32_e32 v100, 16, v101
	v_and_b32_e32 v101, 0xffff0000, v101
	v_lshlrev_b32_e32 v116, 16, v104
	v_and_b32_e32 v117, 0xffff0000, v104
	v_lshlrev_b32_e32 v104, 16, v105
	v_and_b32_e32 v105, 0xffff0000, v105
	v_pk_add_f32 v[56:57], v[56:57], v[110:111]
	v_lshlrev_b32_e32 v98, 16, v99
	v_and_b32_e32 v99, 0xffff0000, v99
	v_pk_add_f32 v[60:61], v[60:61], v[108:109]
	v_pk_add_f32 v[58:59], v[58:59], v[100:101]
	v_pk_add_f32 v[100:101], v[50:51], v[104:105]
	v_cvt_pk_bf16_f32 v50, v56, v57
	v_pk_mul_f32 v[56:57], v[56:57], v[56:57]
	v_pk_add_f32 v[62:63], v[62:63], v[98:99]
	v_cvt_pk_bf16_f32 v51, v58, v59
	v_pk_mul_f32 v[58:59], v[58:59], v[58:59]
	v_pk_fma_f32 v[56:57], v[60:61], v[60:61], v[56:57]
	v_lshlrev_b32_e32 v114, 16, v102
	v_and_b32_e32 v115, 0xffff0000, v102
	v_lshlrev_b32_e32 v102, 16, v103
	v_and_b32_e32 v103, 0xffff0000, v103
	v_pk_add_f32 v[98:99], v[48:49], v[116:117]
	v_pk_fma_f32 v[58:59], v[62:63], v[62:63], v[58:59]
	v_add_f32_e32 v56, v56, v57
	v_pk_add_f32 v[52:53], v[52:53], v[114:115]
	v_pk_add_f32 v[54:55], v[54:55], v[102:103]
	v_pk_mul_f32 v[102:103], v[98:99], v[98:99]
	v_add_f32_e32 v56, v58, v56
	v_cvt_pk_bf16_f32 v48, v60, v61
	v_pk_fma_f32 v[60:61], v[52:53], v[52:53], v[102:103]
	v_add_f32_e32 v56, v59, v56
	v_pk_mul_f32 v[104:105], v[100:101], v[100:101]
	v_add_f32_e32 v56, v60, v56
	v_cvt_pk_bf16_f32 v49, v62, v63
	v_pk_fma_f32 v[62:63], v[54:55], v[54:55], v[104:105]
	v_add_f32_e32 v56, v61, v56
	v_add_f32_e32 v56, v62, v56
	v_add_f32_e32 v58, v63, v56
	ds_bpermute_b32 v59, v204, v58
	v_lshl_add_u64 v[56:57], v[152:153], 0, v[106:107]
	v_lshl_add_u64 v[56:57], v[180:181], 1, v[56:57]
	global_store_dwordx4 v[56:57], v[48:51], off
	s_waitcnt lgkmcnt(0)
	s_nop 0
	v_add_f32_e32 v48, v58, v59
	ds_bpermute_b32 v49, v112, v48
	v_cvt_pk_bf16_f32 v50, v52, v53
	v_cvt_pk_bf16_f32 v51, v54, v55
	v_cvt_pk_bf16_f32 v52, v98, v99
	v_cvt_pk_bf16_f32 v53, v100, v101
	global_store_dwordx4 v[56:57], v[50:53], off offset:256
	s_and_saveexec_b64 s[28:29], s[6:7]
	s_cbranch_execz .LBB0_953
	s_waitcnt lgkmcnt(0)
	v_add_f32_e32 v50, v48, v49
	v_lshlrev_b64 v[48:49], 6, v[96:97]
	v_lshl_add_u64 v[48:49], v[154:155], 0, v[48:49]
	v_lshl_add_u64 v[48:49], s[12:13], 2, v[48:49]
	s_lshl_b32 s20, s46, 2
	v_lshl_add_u64 v[48:49], v[48:49], 0, s[20:21]
	global_store_dword v[48:49], v50, off
; #define GAS __attribute__((address_space(1)))
; __device__ __forceinline__ float sigmoidf_fast(float z) { return fast_rcp(1.f + fast_exp2(-z * LOG2E)); }
; __device__ __forceinline__ float bf_lo(unsigned w) { return __uint_as_float(w << 16); }
; __device__ __forceinline__ float bf_hi(unsigned w) { return __uint_as_float(w & 0xffff0000u); }
;   __device__ __forceinline__ void operator()(ACC_T, const Unit& u, int wr, int wc, int fr, int fq) const {
;     ...
; #pragma unroll
;       for (int k = 0; k < NB; ++k) {
;         const int st = b0 + k, ri = st >> 1, bj = st & 1, ai = ri >> 2, m = ri & 3;
;         const int row = erow(u, ai, wr, m, fr);
;         const u32x4 hnx = hq[k];
;         f32x4 h0, h1;
;         h0[0] = bf_lo(hnx.x); h0[1] = bf_hi(hnx.x); h0[2] = bf_lo(hnx.y); h0[3] = bf_hi(hnx.y);
;         h1[0] = bf_lo(hnx.z); h1[1] = bf_hi(hnx.z); h1[2] = bf_lo(hnx.w); h1[3] = bf_hi(hnx.w);
;         const float rg = GATED ? rs[ai][m] : 0.f;
;         const size_t off = (size_t)row * DM + cbase + 128 * bj;
;         float pr[8];
;         if (GATED) {
;           const u32x4 pw = pq[k];
;           pr[0] = bf_lo(pw.x); pr[1] = bf_hi(pw.x); pr[2] = bf_lo(pw.y); pr[3] = bf_hi(pw.y);
;           pr[4] = bf_lo(pw.z); pr[5] = bf_hi(pw.z); pr[6] = bf_lo(pw.w); pr[7] = bf_hi(pw.w);
;         }
;         f32x4 v0, v1;
; #pragma unroll
;         for (int j = 0; j < 4; ++j) {
;           const float a0 = acc[ai][bj][m][0][j], a1 = acc[ai][bj][m][1][j];
;           const float d0 = GATED ? sigmoidf_fast(a0 * rg) * pr[j] : scale * a0;
;           const float d1 = GATED ? sigmoidf_fast(a1 * rg) * pr[4 + j] : scale * a1;
;           v0[j] = h0[j] + d0; v1[j] = h1[j] + d1;
;           ss += v0[j] * v0[j] + v1[j] * v1[j];
;         }
;         *(GAS u32x4*)(hb + off) = pack8(v0, v1, 1.f);
;         if (bj == 1) {
;           ss += __shfl_xor(ss, 16); ss += __shfl_xor(ss, 32);
;           if (fq == 0) ((GAS float*)ssq_out)[(size_t)row * 16 + 4 * u.pn + wc] = ss;
;           ss = 0.f;
;         }
.LBB0_953:
	s_or_b64 exec, exec, s[28:29]
	v_lshlrev_b32_e32 v48, 16, v84
	s_waitcnt lgkmcnt(0)
	v_and_b32_e32 v49, 0xffff0000, v84
	v_lshlrev_b32_e32 v52, 16, v80
	v_and_b32_e32 v53, 0xffff0000, v80
	v_pk_add_f32 v[44:45], v[44:45], v[48:49]
	v_lshlrev_b32_e32 v48, 16, v86
	v_and_b32_e32 v49, 0xffff0000, v86
	v_pk_add_f32 v[36:37], v[36:37], v[52:53]
	v_lshlrev_b32_e32 v52, 16, v82
	v_and_b32_e32 v53, 0xffff0000, v82
	v_pk_add_f32 v[48:49], v[40:41], v[48:49]
	v_lshlrev_b32_e32 v40, 16, v85
	v_and_b32_e32 v41, 0xffff0000, v85
	v_pk_add_f32 v[52:53], v[32:33], v[52:53]
	v_lshlrev_b32_e32 v32, 16, v81
	v_and_b32_e32 v33, 0xffff0000, v81
	v_pk_add_f32 v[46:47], v[46:47], v[40:41]
	v_lshlrev_b32_e32 v40, 16, v87
	v_and_b32_e32 v41, 0xffff0000, v87
	v_pk_add_f32 v[38:39], v[38:39], v[32:33]
	v_lshlrev_b32_e32 v32, 16, v83
	v_and_b32_e32 v33, 0xffff0000, v83
	v_pk_add_f32 v[50:51], v[42:43], v[40:41]
	v_pk_add_f32 v[54:55], v[34:35], v[32:33]
	v_pk_mul_f32 v[32:33], v[48:49], v[48:49]
	v_pk_mul_f32 v[34:35], v[50:51], v[50:51]
	v_pk_fma_f32 v[32:33], v[44:45], v[44:45], v[32:33]
	v_pk_fma_f32 v[34:35], v[46:47], v[46:47], v[34:35]
	v_add_f32_e32 v32, v32, v33
	v_cvt_pk_bf16_f32 v40, v44, v45
	v_pk_mul_f32 v[44:45], v[52:53], v[52:53]
	v_add_f32_e32 v32, v34, v32
	v_pk_fma_f32 v[44:45], v[36:37], v[36:37], v[44:45]
	v_add_f32_e32 v32, v35, v32
	v_cvt_pk_bf16_f32 v41, v46, v47
	v_pk_mul_f32 v[46:47], v[54:55], v[54:55]
	v_add_f32_e32 v32, v44, v32
	v_pk_fma_f32 v[46:47], v[38:39], v[38:39], v[46:47]
	v_add_f32_e32 v32, v45, v32
	v_add_f32_e32 v32, v46, v32
	v_add_f32_e32 v35, v47, v32
	ds_bpermute_b32 v46, v204, v35
	v_lshl_add_u64 v[32:33], v[152:153], 0, v[94:95]
	v_lshl_add_u64 v[44:45], v[180:181], 1, v[32:33]
	v_cvt_pk_bf16_f32 v42, v48, v49
	v_cvt_pk_bf16_f32 v43, v50, v51
	s_waitcnt lgkmcnt(0)
	v_add_f32_e32 v32, v35, v46
	ds_bpermute_b32 v33, v112, v32
	v_cvt_pk_bf16_f32 v34, v36, v37
	v_cvt_pk_bf16_f32 v35, v38, v39
	v_cvt_pk_bf16_f32 v36, v52, v53
	v_cvt_pk_bf16_f32 v37, v54, v55
	global_store_dwordx4 v[44:45], v[40:43], off
	global_store_dwordx4 v[44:45], v[34:37], off offset:256
	s_and_saveexec_b64 s[28:29], s[6:7]
	s_cbranch_execz .LBB0_955
	s_waitcnt lgkmcnt(0)
	v_add_f32_e32 v34, v32, v33
	v_lshlrev_b64 v[32:33], 6, v[92:93]
	v_lshl_add_u64 v[32:33], v[154:155], 0, v[32:33]
	v_lshl_add_u64 v[32:33], s[12:13], 2, v[32:33]
	s_lshl_b32 s20, s46, 2
	v_lshl_add_u64 v[32:33], v[32:33], 0, s[20:21]
	global_store_dword v[32:33], v34, off
.LBB0_955:
	s_or_b64 exec, exec, s[28:29]
	v_lshlrev_b32_e32 v32, 16, v76
	s_waitcnt lgkmcnt(0)
	v_and_b32_e32 v33, 0xffff0000, v76
	v_lshlrev_b32_e32 v38, 16, v72
	v_and_b32_e32 v39, 0xffff0000, v72
	v_pk_add_f32 v[28:29], v[28:29], v[32:33]
	v_lshlrev_b32_e32 v32, 16, v78
	v_and_b32_e32 v33, 0xffff0000, v78
	v_pk_add_f32 v[20:21], v[20:21], v[38:39]
	v_lshlrev_b32_e32 v38, 16, v74
	v_and_b32_e32 v39, 0xffff0000, v74
	v_pk_add_f32 v[32:33], v[24:25], v[32:33]
	v_lshlrev_b32_e32 v24, 16, v77
	v_and_b32_e32 v25, 0xffff0000, v77
	v_pk_add_f32 v[38:39], v[16:17], v[38:39]
	v_lshlrev_b32_e32 v16, 16, v73
	v_and_b32_e32 v17, 0xffff0000, v73
	v_pk_add_f32 v[30:31], v[30:31], v[24:25]
	v_lshlrev_b32_e32 v24, 16, v79
	v_and_b32_e32 v25, 0xffff0000, v79
	v_pk_add_f32 v[22:23], v[22:23], v[16:17]
	v_lshlrev_b32_e32 v16, 16, v75
	v_and_b32_e32 v17, 0xffff0000, v75
	v_pk_add_f32 v[34:35], v[26:27], v[24:25]
	v_pk_add_f32 v[40:41], v[18:19], v[16:17]
	v_pk_mul_f32 v[16:17], v[32:33], v[32:33]
	v_pk_mul_f32 v[18:19], v[34:35], v[34:35]
	v_pk_fma_f32 v[16:17], v[28:29], v[28:29], v[16:17]
	v_pk_fma_f32 v[18:19], v[30:31], v[30:31], v[18:19]
	v_add_f32_e32 v16, v16, v17
	v_cvt_pk_bf16_f32 v24, v28, v29
	v_pk_mul_f32 v[28:29], v[38:39], v[38:39]
	v_add_f32_e32 v16, v18, v16
	v_pk_fma_f32 v[28:29], v[20:21], v[20:21], v[28:29]
	v_add_f32_e32 v16, v19, v16
	v_cvt_pk_bf16_f32 v25, v30, v31
	v_pk_mul_f32 v[30:31], v[40:41], v[40:41]
	v_add_f32_e32 v16, v28, v16
	v_pk_fma_f32 v[30:31], v[22:23], v[22:23], v[30:31]
	v_add_f32_e32 v16, v29, v16
	v_add_f32_e32 v16, v30, v16
	v_add_f32_e32 v19, v31, v16
	ds_bpermute_b32 v30, v204, v19
	v_lshlrev_b64 v[36:37], 11, v[90:91]
	v_lshl_add_u64 v[16:17], v[152:153], 0, v[36:37]
	v_lshl_add_u64 v[28:29], v[180:181], 1, v[16:17]
	v_cvt_pk_bf16_f32 v26, v32, v33
	s_waitcnt lgkmcnt(0)
	v_add_f32_e32 v16, v19, v30
	ds_bpermute_b32 v17, v112, v16
	v_cvt_pk_bf16_f32 v27, v34, v35
	v_cvt_pk_bf16_f32 v18, v20, v21
	v_cvt_pk_bf16_f32 v19, v22, v23
	v_cvt_pk_bf16_f32 v20, v38, v39
	v_cvt_pk_bf16_f32 v21, v40, v41
	global_store_dwordx4 v[28:29], v[24:27], off
	global_store_dwordx4 v[28:29], v[18:21], off offset:256
	s_and_saveexec_b64 s[28:29], s[6:7]
	s_cbranch_execz .LBB0_957
	s_waitcnt lgkmcnt(0)
	v_add_f32_e32 v18, v16, v17
	v_lshlrev_b64 v[16:17], 6, v[90:91]
	v_lshl_add_u64 v[16:17], v[154:155], 0, v[16:17]
	v_lshl_add_u64 v[16:17], s[12:13], 2, v[16:17]
	s_lshl_b32 s20, s46, 2
	v_lshl_add_u64 v[16:17], v[16:17], 0, s[20:21]
	global_store_dword v[16:17], v18, off

; #define GAS __attribute__((address_space(1)))
; __device__ __forceinline__ float sigmoidf_fast(float z) { return fast_rcp(1.f + fast_exp2(-z * LOG2E)); }
; __device__ __forceinline__ float bf_lo(unsigned w) { return __uint_as_float(w << 16); }
;   __device__ __forceinline__ void operator()(ACC_T, const Unit& u, int wr, int wc, int fr, int fq) const {
;     ...
;     for (int b0 = 0; b0 < 16; b0 += NB) {
;       u32x4 hq[NB], pq[GATED ? NB : 1];
; #pragma unroll
;       for (int k = 0; k < NB; ++k) {
;         const int st = b0 + k, ri = st >> 1;
;         const size_t off = (size_t)erow(u, ri >> 2, wr, ri & 3, fr) * DM + cbase + 128 * (st & 1);
;         hq[k] = *(GAS const u32x4*)(hres + off);
;         if (GATED) pq[k] = *(GAS const u32x4*)(projb + off);
;       }
; #pragma unroll
;       for (int k = 0; k < NB; ++k) {
;         const int st = b0 + k, ri = st >> 1, bj = st & 1, ai = ri >> 2, m = ri & 3;
;         const int row = erow(u, ai, wr, m, fr);
;         const u32x4 hnx = hq[k];
;         f32x4 h0, h1;
;         h0[0] = bf_lo(hnx.x); h0[1] = bf_hi(hnx.x); h0[2] = bf_lo(hnx.y); h0[3] = bf_hi(hnx.y);
;         h1[0] = bf_lo(hnx.z); h1[1] = bf_hi(hnx.z); h1[2] = bf_lo(hnx.w); h1[3] = bf_hi(hnx.w);
;         const float rg = GATED ? rs[ai][m] : 0.f;
;         const size_t off = (size_t)row * DM + cbase + 128 * bj;
;         float pr[8];
;         if (GATED) {
;           const u32x4 pw = pq[k];
;           pr[0] = bf_lo(pw.x); pr[1] = bf_hi(pw.x); pr[2] = bf_lo(pw.y); pr[3] = bf_hi(pw.y);
;           pr[4] = bf_lo(pw.z); pr[5] = bf_hi(pw.z); pr[6] = bf_lo(pw.w); pr[7] = bf_hi(pw.w);
;         }
;         f32x4 v0, v1;
; #pragma unroll
;         for (int j = 0; j < 4; ++j) {
;           const float a0 = acc[ai][bj][m][0][j], a1 = acc[ai][bj][m][1][j];
;           const float d0 = GATED ? sigmoidf_fast(a0 * rg) * pr[j] : scale * a0;
;           const float d1 = GATED ? sigmoidf_fast(a1 * rg) * pr[4 + j] : scale * a1;
;           v0[j] = h0[j] + d0; v1[j] = h1[j] + d1;
;           ss += v0[j] * v0[j] + v1[j] * v1[j];
;         }
;         *(GAS u32x4*)(hb + off) = pack8(v0, v1, 1.f);
;         if (bj == 1) {
;           ss += __shfl_xor(ss, 16); ss += __shfl_xor(ss, 32);
;           if (fq == 0) ((GAS float*)ssq_out)[(size_t)row * 16 + 4 * u.pn + wc] = ss;
;           ss = 0.f;
;         }
.LBB0_1091:
	v_lshl_or_b32 v180, s20, 8, v200
	v_lshl_add_u32 v184, s28, 8, v198
	v_ashrrev_i32_e32 v181, 31, v180
	v_lshlrev_b64 v[214:215], 1, v[180:181]
	v_ashrrev_i32_e32 v185, 31, v184
	v_lshl_add_u64 v[182:183], v[152:153], 0, v[214:215]
	v_lshlrev_b64 v[204:205], 11, v[184:185]
	v_lshl_add_u64 v[128:129], v[182:183], 0, v[204:205]
	global_load_dwordx4 v[206:209], v[128:129], off
	global_load_dwordx4 v[210:213], v[128:129], off offset:256
	v_or_b32_e32 v194, 16, v184
	v_or_b32_e32 v190, 32, v184
	v_or_b32_e32 v186, 48, v184
	v_ashrrev_i32_e32 v195, 31, v194
	v_ashrrev_i32_e32 v191, 31, v190
	v_ashrrev_i32_e32 v187, 31, v186
	v_lshlrev_b64 v[196:197], 11, v[194:195]
	v_lshlrev_b64 v[192:193], 11, v[190:191]
	v_lshlrev_b64 v[188:189], 11, v[186:187]
	v_lshl_add_u64 v[128:129], v[182:183], 0, v[196:197]
	v_lshl_add_u64 v[130:131], v[182:183], 0, v[192:193]
	v_lshl_add_u64 v[216:217], v[182:183], 0, v[188:189]
	global_load_dwordx4 v[148:151], v[128:129], off
	global_load_dwordx4 v[144:147], v[128:129], off offset:256
	global_load_dwordx4 v[140:143], v[130:131], off
	global_load_dwordx4 v[136:139], v[130:131], off offset:256
	global_load_dwordx4 v[132:135], v[216:217], off
	s_nop 0
	global_load_dwordx4 v[128:131], v[216:217], off offset:256
	v_add_u32_e32 v226, 0x80, v184
	v_ashrrev_i32_e32 v227, 31, v226
	v_lshlrev_b64 v[226:227], 11, v[226:227]
	v_lshl_add_u64 v[252:253], v[182:183], 0, v[226:227]
	global_load_dwordx4 v[228:231], v[252:253], off
	global_load_dwordx4 v[232:235], v[252:253], off offset:256
	v_add_u32_e32 v226, 0x90, v184
	v_ashrrev_i32_e32 v227, 31, v226
	v_lshlrev_b64 v[226:227], 11, v[226:227]
	v_lshl_add_u64 v[252:253], v[182:183], 0, v[226:227]
	global_load_dwordx4 v[236:239], v[252:253], off
	global_load_dwordx4 v[240:243], v[252:253], off offset:256
	v_add_u32_e32 v226, 0xa0, v184
	v_ashrrev_i32_e32 v227, 31, v226
	v_lshlrev_b64 v[226:227], 11, v[226:227]
	v_lshl_add_u64 v[252:253], v[182:183], 0, v[226:227]
	global_load_dwordx4 v[244:247], v[252:253], off
	global_load_dwordx4 v[248:251], v[252:253], off offset:256
	v_and_b32_e32 v217, 64, v203
	v_xor_b32_e32 v216, 16, v203
	v_add_u32_e32 v217, 64, v217
	v_xor_b32_e32 v218, 32, v203
	v_cmp_lt_i32_e32 vcc, v216, v217
	s_lshl_b32 s12, s20, 2
	s_ashr_i32 s13, s12, 31
	v_cndmask_b32_e32 v219, v203, v216, vcc
	v_cmp_lt_i32_e32 vcc, v218, v217
	v_lshl_add_u64 v[216:217], v[152:153], 0, v[204:205]
	v_lshlrev_b32_e32 v204, 2, v219
	v_cndmask_b32_e32 v224, v203, v218, vcc
	v_lshl_add_u64 v[214:215], v[216:217], 0, v[214:215]
	s_waitcnt vmcnt(6)
	v_lshlrev_b32_e32 v218, 16, v208
	v_and_b32_e32 v219, 0xffff0000, v208
	v_lshlrev_b32_e32 v216, 16, v206
	v_and_b32_e32 v217, 0xffff0000, v206
	v_lshlrev_b32_e32 v208, 16, v209
	v_and_b32_e32 v209, 0xffff0000, v209
	v_lshlrev_b32_e32 v222, 16, v212
	v_and_b32_e32 v223, 0xffff0000, v212
	v_lshlrev_b32_e32 v212, 16, v213
	v_and_b32_e32 v213, 0xffff0000, v213
	v_pk_fma_f32 v[124:125], v[124:125], 0.5, v[218:219] op_sel_hi:[1,0,1]
	v_lshlrev_b32_e32 v206, 16, v207
	v_and_b32_e32 v207, 0xffff0000, v207
	v_lshlrev_b32_e32 v220, 16, v210
	v_and_b32_e32 v221, 0xffff0000, v210
	v_lshlrev_b32_e32 v210, 16, v211
	v_and_b32_e32 v211, 0xffff0000, v211
	v_pk_fma_f32 v[120:121], v[120:121], 0.5, v[216:217] op_sel_hi:[1,0,1]
	v_pk_fma_f32 v[126:127], v[126:127], 0.5, v[208:209] op_sel_hi:[1,0,1]
	v_pk_fma_f32 v[208:209], v[114:115], 0.5, v[212:213] op_sel_hi:[1,0,1]
	v_pk_mul_f32 v[114:115], v[124:125], v[124:125]
	v_pk_fma_f32 v[122:123], v[122:123], 0.5, v[206:207] op_sel_hi:[1,0,1]
	v_pk_fma_f32 v[118:119], v[118:119], 0.5, v[210:211] op_sel_hi:[1,0,1]
	v_pk_mul_f32 v[210:211], v[126:127], v[126:127]
	v_pk_fma_f32 v[114:115], v[120:121], v[120:121], v[114:115]
	v_pk_fma_f32 v[206:207], v[112:113], 0.5, v[222:223] op_sel_hi:[1,0,1]
	v_cvt_pk_bf16_f32 v112, v120, v121
	v_pk_fma_f32 v[120:121], v[122:123], v[122:123], v[210:211]
	v_add_f32_e32 v114, v114, v115
	v_pk_fma_f32 v[116:117], v[116:117], 0.5, v[220:221] op_sel_hi:[1,0,1]
	v_pk_mul_f32 v[212:213], v[206:207], v[206:207]
	v_add_f32_e32 v114, v120, v114
	v_cvt_pk_bf16_f32 v113, v122, v123
	v_pk_fma_f32 v[122:123], v[116:117], v[116:117], v[212:213]
	v_add_f32_e32 v114, v121, v114
	v_pk_mul_f32 v[216:217], v[208:209], v[208:209]
	v_add_f32_e32 v114, v122, v114
	v_pk_fma_f32 v[210:211], v[118:119], v[118:119], v[216:217]
	v_add_f32_e32 v114, v123, v114
	v_add_f32_e32 v114, v210, v114
	v_add_f32_e32 v120, v211, v114
	ds_bpermute_b32 v121, v204, v120
	v_cvt_pk_bf16_f32 v114, v124, v125
	v_cvt_pk_bf16_f32 v115, v126, v127
	global_store_dwordx4 v[214:215], v[112:115], off
	v_cvt_pk_bf16_f32 v116, v116, v117
	v_cvt_pk_bf16_f32 v117, v118, v119
	s_waitcnt lgkmcnt(0)
	v_add_f32_e32 v113, v120, v121
	v_lshlrev_b32_e32 v112, 2, v224
	ds_bpermute_b32 v114, v112, v113
	v_cvt_pk_bf16_f32 v118, v206, v207
	v_cvt_pk_bf16_f32 v119, v208, v209
	global_store_dwordx4 v[214:215], v[116:119], off offset:256
	s_and_saveexec_b64 s[28:29], s[6:7]
	s_cbranch_execz .LBB0_1093
	s_waitcnt lgkmcnt(0)
	v_add_f32_e32 v113, v113, v114
	v_lshlrev_b64 v[114:115], 6, v[184:185]
	v_lshl_add_u64 v[114:115], v[154:155], 0, v[114:115]
	v_lshl_add_u64 v[114:115], s[12:13], 2, v[114:115]
	s_lshl_b32 s20, s46, 2
	v_lshl_add_u64 v[114:115], v[114:115], 0, s[20:21]
	global_store_dword v[114:115], v113, off

; #define GAS __attribute__((address_space(1)))
; __device__ __forceinline__ float sigmoidf_fast(float z) { return fast_rcp(1.f + fast_exp2(-z * LOG2E)); }
; __device__ __forceinline__ float bf_lo(unsigned w) { return __uint_as_float(w << 16); }
; __device__ __forceinline__ float bf_hi(unsigned w) { return __uint_as_float(w & 0xffff0000u); }
;   __device__ __forceinline__ void operator()(ACC_T, const Unit& u, int wr, int wc, int fr, int fq) const {
;     ...
; #pragma unroll
;       for (int k = 0; k < NB; ++k) {
;         const int st = b0 + k, ri = st >> 1;
;         const size_t off = (size_t)erow(u, ri >> 2, wr, ri & 3, fr) * DM + cbase + 128 * (st & 1);
;         hq[k] = *(GAS const u32x4*)(hres + off);
;         if (GATED) pq[k] = *(GAS const u32x4*)(projb + off);
;       }
; #pragma unroll
;       for (int k = 0; k < NB; ++k) {
;         const int st = b0 + k, ri = st >> 1, bj = st & 1, ai = ri >> 2, m = ri & 3;
;         const int row = erow(u, ai, wr, m, fr);
;         const u32x4 hnx = hq[k];
;         f32x4 h0, h1;
;         h0[0] = bf_lo(hnx.x); h0[1] = bf_hi(hnx.x); h0[2] = bf_lo(hnx.y); h0[3] = bf_hi(hnx.y);
;         h1[0] = bf_lo(hnx.z); h1[1] = bf_hi(hnx.z); h1[2] = bf_lo(hnx.w); h1[3] = bf_hi(hnx.w);
;         const float rg = GATED ? rs[ai][m] : 0.f;
;         const size_t off = (size_t)row * DM + cbase + 128 * bj;
;         float pr[8];
;         if (GATED) {
;           const u32x4 pw = pq[k];
;           pr[0] = bf_lo(pw.x); pr[1] = bf_hi(pw.x); pr[2] = bf_lo(pw.y); pr[3] = bf_hi(pw.y);
;           pr[4] = bf_lo(pw.z); pr[5] = bf_hi(pw.z); pr[6] = bf_lo(pw.w); pr[7] = bf_hi(pw.w);
;         }
;         f32x4 v0, v1;
; #pragma unroll
;         for (int j = 0; j < 4; ++j) {
;           const float a0 = acc[ai][bj][m][0][j], a1 = acc[ai][bj][m][1][j];
;           const float d0 = GATED ? sigmoidf_fast(a0 * rg) * pr[j] : scale * a0;
;           const float d1 = GATED ? sigmoidf_fast(a1 * rg) * pr[4 + j] : scale * a1;
;           v0[j] = h0[j] + d0; v1[j] = h1[j] + d1;
;           ss += v0[j] * v0[j] + v1[j] * v1[j];
;         }
;         *(GAS u32x4*)(hb + off) = pack8(v0, v1, 1.f);
;         if (bj == 1) {
;           ss += __shfl_xor(ss, 16); ss += __shfl_xor(ss, 32);
;           if (fq == 0) ((GAS float*)ssq_out)[(size_t)row * 16 + 4 * u.pn + wc] = ss;
;           ss = 0.f;
;         }
.LBB0_1099:
	s_or_b64 exec, exec, s[28:29]
	v_add_u32_e32 v96, 0x80, v184
	v_ashrrev_i32_e32 v97, 31, v96
	v_lshlrev_b64 v[106:107], 11, v[96:97]
	s_waitcnt lgkmcnt(0)
	v_lshl_add_u64 v[64:65], v[182:183], 0, v[106:107]
	s_waitcnt vmcnt(8)
	v_mov_b32_e32 v98, v228
	v_mov_b32_e32 v99, v229
	v_mov_b32_e32 v100, v230
	v_mov_b32_e32 v101, v231
	v_mov_b32_e32 v102, v232
	v_mov_b32_e32 v103, v233
	v_mov_b32_e32 v104, v234
	v_mov_b32_e32 v105, v235
	v_add_u32_e32 v92, 0x90, v184
	v_add_u32_e32 v90, 0xa0, v184
	v_add_u32_e32 v88, 0xb0, v184
	v_ashrrev_i32_e32 v93, 31, v92
	v_ashrrev_i32_e32 v91, 31, v90
	v_ashrrev_i32_e32 v89, 31, v88
	v_lshlrev_b64 v[94:95], 11, v[92:93]
	v_lshlrev_b64 v[64:65], 11, v[90:91]
	v_lshlrev_b64 v[66:67], 11, v[88:89]
	v_lshl_add_u64 v[68:69], v[182:183], 0, v[94:95]
	v_lshl_add_u64 v[64:65], v[182:183], 0, v[64:65]
	v_lshl_add_u64 v[66:67], v[182:183], 0, v[66:67]
	v_mov_b32_e32 v84, v236
	v_mov_b32_e32 v85, v237
	v_mov_b32_e32 v86, v238
	v_mov_b32_e32 v87, v239
	v_mov_b32_e32 v80, v240
	v_mov_b32_e32 v81, v241
	v_mov_b32_e32 v82, v242
	v_mov_b32_e32 v83, v243
	v_mov_b32_e32 v76, v244
	v_mov_b32_e32 v77, v245
	v_mov_b32_e32 v78, v246
	v_mov_b32_e32 v79, v247
	v_mov_b32_e32 v72, v248
	v_mov_b32_e32 v73, v249
	v_mov_b32_e32 v74, v250
	v_mov_b32_e32 v75, v251
	s_nop 0
	global_load_dwordx4 v[68:71], v[66:67], off
	s_nop 0
	global_load_dwordx4 v[64:67], v[66:67], off offset:256
	v_lshlrev_b32_e32 v110, 16, v100
	v_and_b32_e32 v111, 0xffff0000, v100
	v_lshlrev_b32_e32 v108, 16, v98
	v_and_b32_e32 v109, 0xffff0000, v98
	v_lshlrev_b32_e32 v100, 16, v101
	v_and_b32_e32 v101, 0xffff0000, v101
	v_lshlrev_b32_e32 v116, 16, v104
	v_and_b32_e32 v117, 0xffff0000, v104
	v_lshlrev_b32_e32 v104, 16, v105
	v_and_b32_e32 v105, 0xffff0000, v105
	v_pk_fma_f32 v[56:57], v[56:57], 0.5, v[110:111] op_sel_hi:[1,0,1]
	v_lshlrev_b32_e32 v98, 16, v99
	v_and_b32_e32 v99, 0xffff0000, v99
	v_pk_fma_f32 v[60:61], v[60:61], 0.5, v[108:109] op_sel_hi:[1,0,1]
	v_pk_fma_f32 v[58:59], v[58:59], 0.5, v[100:101] op_sel_hi:[1,0,1]
	v_pk_fma_f32 v[100:101], v[50:51], 0.5, v[104:105] op_sel_hi:[1,0,1]
	v_cvt_pk_bf16_f32 v50, v56, v57
	v_pk_mul_f32 v[56:57], v[56:57], v[56:57]
	v_pk_fma_f32 v[62:63], v[62:63], 0.5, v[98:99] op_sel_hi:[1,0,1]
	v_cvt_pk_bf16_f32 v51, v58, v59
	v_pk_mul_f32 v[58:59], v[58:59], v[58:59]
	v_pk_fma_f32 v[56:57], v[60:61], v[60:61], v[56:57]
	v_lshlrev_b32_e32 v114, 16, v102
	v_and_b32_e32 v115, 0xffff0000, v102
	v_lshlrev_b32_e32 v102, 16, v103
	v_and_b32_e32 v103, 0xffff0000, v103
	v_pk_fma_f32 v[98:99], v[48:49], 0.5, v[116:117] op_sel_hi:[1,0,1]
	v_pk_fma_f32 v[58:59], v[62:63], v[62:63], v[58:59]
	v_add_f32_e32 v56, v56, v57
	v_pk_fma_f32 v[52:53], v[52:53], 0.5, v[114:115] op_sel_hi:[1,0,1]
	v_pk_fma_f32 v[54:55], v[54:55], 0.5, v[102:103] op_sel_hi:[1,0,1]
	v_pk_mul_f32 v[102:103], v[98:99], v[98:99]
	v_add_f32_e32 v56, v58, v56
	v_cvt_pk_bf16_f32 v48, v60, v61
	v_pk_fma_f32 v[60:61], v[52:53], v[52:53], v[102:103]
	v_add_f32_e32 v56, v59, v56
	v_pk_mul_f32 v[104:105], v[100:101], v[100:101]
	v_add_f32_e32 v56, v60, v56
	v_cvt_pk_bf16_f32 v49, v62, v63
	v_pk_fma_f32 v[62:63], v[54:55], v[54:55], v[104:105]
	v_add_f32_e32 v56, v61, v56
	v_add_f32_e32 v56, v62, v56
	v_add_f32_e32 v58, v63, v56
	ds_bpermute_b32 v59, v204, v58
	v_lshl_add_u64 v[56:57], v[152:153], 0, v[106:107]
	v_lshl_add_u64 v[56:57], v[180:181], 1, v[56:57]
	global_store_dwordx4 v[56:57], v[48:51], off
	s_waitcnt lgkmcnt(0)
	s_nop 0
	v_add_f32_e32 v48, v58, v59
	ds_bpermute_b32 v49, v112, v48
	v_cvt_pk_bf16_f32 v50, v52, v53
	v_cvt_pk_bf16_f32 v51, v54, v55
	v_cvt_pk_bf16_f32 v52, v98, v99
	v_cvt_pk_bf16_f32 v53, v100, v101
	global_store_dwordx4 v[56:57], v[50:53], off offset:256
	s_and_saveexec_b64 s[28:29], s[6:7]
	s_cbranch_execz .LBB0_1101
	s_waitcnt lgkmcnt(0)
	v_add_f32_e32 v50, v48, v49
	v_lshlrev_b64 v[48:49], 6, v[96:97]
	v_lshl_add_u64 v[48:49], v[154:155], 0, v[48:49]
	v_lshl_add_u64 v[48:49], s[12:13], 2, v[48:49]
	s_lshl_b32 s20, s46, 2
	v_lshl_add_u64 v[48:49], v[48:49], 0, s[20:21]
	global_store_dword v[48:49], v50, off
; #define GAS __attribute__((address_space(1)))
; __device__ __forceinline__ float sigmoidf_fast(float z) { return fast_rcp(1.f + fast_exp2(-z * LOG2E)); }
; __device__ __forceinline__ float bf_lo(unsigned w) { return __uint_as_float(w << 16); }
; __device__ __forceinline__ float bf_hi(unsigned w) { return __uint_as_float(w & 0xffff0000u); }
;   __device__ __forceinline__ void operator()(ACC_T, const Unit& u, int wr, int wc, int fr, int fq) const {
;     ...
; #pragma unroll
;       for (int k = 0; k < NB; ++k) {
;         const int st = b0 + k, ri = st >> 1, bj = st & 1, ai = ri >> 2, m = ri & 3;
;         const int row = erow(u, ai, wr, m, fr);
;         const u32x4 hnx = hq[k];
;         f32x4 h0, h1;
;         h0[0] = bf_lo(hnx.x); h0[1] = bf_hi(hnx.x); h0[2] = bf_lo(hnx.y); h0[3] = bf_hi(hnx.y);
;         h1[0] = bf_lo(hnx.z); h1[1] = bf_hi(hnx.z); h1[2] = bf_lo(hnx.w); h1[3] = bf_hi(hnx.w);
;         const float rg = GATED ? rs[ai][m] : 0.f;
;         const size_t off = (size_t)row * DM + cbase + 128 * bj;
;         float pr[8];
;         if (GATED) {
;           const u32x4 pw = pq[k];
;           pr[0] = bf_lo(pw.x); pr[1] = bf_hi(pw.x); pr[2] = bf_lo(pw.y); pr[3] = bf_hi(pw.y);
;           pr[4] = bf_lo(pw.z); pr[5] = bf_hi(pw.z); pr[6] = bf_lo(pw.w); pr[7] = bf_hi(pw.w);
;         }
;         f32x4 v0, v1;
; #pragma unroll
;         for (int j = 0; j < 4; ++j) {
;           const float a0 = acc[ai][bj][m][0][j], a1 = acc[ai][bj][m][1][j];
;           const float d0 = GATED ? sigmoidf_fast(a0 * rg) * pr[j] : scale * a0;
;           const float d1 = GATED ? sigmoidf_fast(a1 * rg) * pr[4 + j] : scale * a1;
;           v0[j] = h0[j] + d0; v1[j] = h1[j] + d1;
;           ss += v0[j] * v0[j] + v1[j] * v1[j];
;         }
;         *(GAS u32x4*)(hb + off) = pack8(v0, v1, 1.f);
;         if (bj == 1) {
;           ss += __shfl_xor(ss, 16); ss += __shfl_xor(ss, 32);
;           if (fq == 0) ((GAS float*)ssq_out)[(size_t)row * 16 + 4 * u.pn + wc] = ss;
;           ss = 0.f;
;         }
.LBB0_1101:
	s_or_b64 exec, exec, s[28:29]
	v_lshlrev_b32_e32 v48, 16, v84
	s_waitcnt lgkmcnt(0)
	v_and_b32_e32 v49, 0xffff0000, v84
	v_lshlrev_b32_e32 v52, 16, v80
	v_and_b32_e32 v53, 0xffff0000, v80
	v_pk_fma_f32 v[44:45], v[44:45], 0.5, v[48:49] op_sel_hi:[1,0,1]
	v_lshlrev_b32_e32 v48, 16, v86
	v_and_b32_e32 v49, 0xffff0000, v86
	v_pk_fma_f32 v[36:37], v[36:37], 0.5, v[52:53] op_sel_hi:[1,0,1]
	v_lshlrev_b32_e32 v52, 16, v82
	v_and_b32_e32 v53, 0xffff0000, v82
	v_pk_fma_f32 v[48:49], v[40:41], 0.5, v[48:49] op_sel_hi:[1,0,1]
	v_lshlrev_b32_e32 v40, 16, v85
	v_and_b32_e32 v41, 0xffff0000, v85
	v_pk_fma_f32 v[52:53], v[32:33], 0.5, v[52:53] op_sel_hi:[1,0,1]
	v_lshlrev_b32_e32 v32, 16, v81
	v_and_b32_e32 v33, 0xffff0000, v81
	v_pk_fma_f32 v[46:47], v[46:47], 0.5, v[40:41] op_sel_hi:[1,0,1]
	v_lshlrev_b32_e32 v40, 16, v87
	v_and_b32_e32 v41, 0xffff0000, v87
	v_pk_fma_f32 v[38:39], v[38:39], 0.5, v[32:33] op_sel_hi:[1,0,1]
	v_lshlrev_b32_e32 v32, 16, v83
	v_and_b32_e32 v33, 0xffff0000, v83
	v_pk_fma_f32 v[50:51], v[42:43], 0.5, v[40:41] op_sel_hi:[1,0,1]
	v_pk_fma_f32 v[54:55], v[34:35], 0.5, v[32:33] op_sel_hi:[1,0,1]
	v_pk_mul_f32 v[32:33], v[48:49], v[48:49]
	v_pk_mul_f32 v[34:35], v[50:51], v[50:51]
	v_pk_fma_f32 v[32:33], v[44:45], v[44:45], v[32:33]
	v_pk_fma_f32 v[34:35], v[46:47], v[46:47], v[34:35]
	v_add_f32_e32 v32, v32, v33
	v_cvt_pk_bf16_f32 v40, v44, v45
	v_pk_mul_f32 v[44:45], v[52:53], v[52:53]
	v_add_f32_e32 v32, v34, v32
	v_pk_fma_f32 v[44:45], v[36:37], v[36:37], v[44:45]
	v_add_f32_e32 v32, v35, v32
	v_cvt_pk_bf16_f32 v41, v46, v47
	v_pk_mul_f32 v[46:47], v[54:55], v[54:55]
	v_add_f32_e32 v32, v44, v32
	v_pk_fma_f32 v[46:47], v[38:39], v[38:39], v[46:47]
	v_add_f32_e32 v32, v45, v32
	v_add_f32_e32 v32, v46, v32
	v_add_f32_e32 v35, v47, v32
	ds_bpermute_b32 v46, v204, v35
	v_lshl_add_u64 v[32:33], v[152:153], 0, v[94:95]
	v_lshl_add_u64 v[44:45], v[180:181], 1, v[32:33]
	v_cvt_pk_bf16_f32 v42, v48, v49
	v_cvt_pk_bf16_f32 v43, v50, v51
	s_waitcnt lgkmcnt(0)
	v_add_f32_e32 v32, v35, v46
	ds_bpermute_b32 v33, v112, v32
	v_cvt_pk_bf16_f32 v34, v36, v37
	v_cvt_pk_bf16_f32 v35, v38, v39
	v_cvt_pk_bf16_f32 v36, v52, v53
	v_cvt_pk_bf16_f32 v37, v54, v55
	global_store_dwordx4 v[44:45], v[40:43], off
	global_store_dwordx4 v[44:45], v[34:37], off offset:256
	s_and_saveexec_b64 s[28:29], s[6:7]
	s_cbranch_execz .LBB0_1103
	s_waitcnt lgkmcnt(0)
	v_add_f32_e32 v34, v32, v33
	v_lshlrev_b64 v[32:33], 6, v[92:93]
	v_lshl_add_u64 v[32:33], v[154:155], 0, v[32:33]
	v_lshl_add_u64 v[32:33], s[12:13], 2, v[32:33]
	s_lshl_b32 s20, s46, 2
	v_lshl_add_u64 v[32:33], v[32:33], 0, s[20:21]
	global_store_dword v[32:33], v34, off
.LBB0_1103:
	s_or_b64 exec, exec, s[28:29]
	v_lshlrev_b32_e32 v32, 16, v76
	s_waitcnt lgkmcnt(0)
	v_and_b32_e32 v33, 0xffff0000, v76
	v_lshlrev_b32_e32 v38, 16, v72
	v_and_b32_e32 v39, 0xffff0000, v72
	v_pk_fma_f32 v[28:29], v[28:29], 0.5, v[32:33] op_sel_hi:[1,0,1]
	v_lshlrev_b32_e32 v32, 16, v78
	v_and_b32_e32 v33, 0xffff0000, v78
	v_pk_fma_f32 v[20:21], v[20:21], 0.5, v[38:39] op_sel_hi:[1,0,1]
	v_lshlrev_b32_e32 v38, 16, v74
	v_and_b32_e32 v39, 0xffff0000, v74
	v_pk_fma_f32 v[32:33], v[24:25], 0.5, v[32:33] op_sel_hi:[1,0,1]
	v_lshlrev_b32_e32 v24, 16, v77
	v_and_b32_e32 v25, 0xffff0000, v77
	v_pk_fma_f32 v[38:39], v[16:17], 0.5, v[38:39] op_sel_hi:[1,0,1]
	v_lshlrev_b32_e32 v16, 16, v73
	v_and_b32_e32 v17, 0xffff0000, v73
	v_pk_fma_f32 v[30:31], v[30:31], 0.5, v[24:25] op_sel_hi:[1,0,1]
	v_lshlrev_b32_e32 v24, 16, v79
	v_and_b32_e32 v25, 0xffff0000, v79
	v_pk_fma_f32 v[22:23], v[22:23], 0.5, v[16:17] op_sel_hi:[1,0,1]
	v_lshlrev_b32_e32 v16, 16, v75
	v_and_b32_e32 v17, 0xffff0000, v75
	v_pk_fma_f32 v[34:35], v[26:27], 0.5, v[24:25] op_sel_hi:[1,0,1]
	v_pk_fma_f32 v[40:41], v[18:19], 0.5, v[16:17] op_sel_hi:[1,0,1]
	v_pk_mul_f32 v[16:17], v[32:33], v[32:33]
	v_pk_mul_f32 v[18:19], v[34:35], v[34:35]
	v_pk_fma_f32 v[16:17], v[28:29], v[28:29], v[16:17]
	v_pk_fma_f32 v[18:19], v[30:31], v[30:31], v[18:19]
	v_add_f32_e32 v16, v16, v17
	v_cvt_pk_bf16_f32 v24, v28, v29
	v_pk_mul_f32 v[28:29], v[38:39], v[38:39]
	v_add_f32_e32 v16, v18, v16
	v_pk_fma_f32 v[28:29], v[20:21], v[20:21], v[28:29]
	v_add_f32_e32 v16, v19, v16
	v_cvt_pk_bf16_f32 v25, v30, v31
	v_pk_mul_f32 v[30:31], v[40:41], v[40:41]
	v_add_f32_e32 v16, v28, v16
	v_pk_fma_f32 v[30:31], v[22:23], v[22:23], v[30:31]
	v_add_f32_e32 v16, v29, v16
	v_add_f32_e32 v16, v30, v16
	v_add_f32_e32 v19, v31, v16
	ds_bpermute_b32 v30, v204, v19
	v_lshlrev_b64 v[36:37], 11, v[90:91]
	v_lshl_add_u64 v[16:17], v[152:153], 0, v[36:37]
	v_lshl_add_u64 v[28:29], v[180:181], 1, v[16:17]
	v_cvt_pk_bf16_f32 v26, v32, v33
	s_waitcnt lgkmcnt(0)
	v_add_f32_e32 v16, v19, v30
	ds_bpermute_b32 v17, v112, v16
	v_cvt_pk_bf16_f32 v27, v34, v35
	v_cvt_pk_bf16_f32 v18, v20, v21
	v_cvt_pk_bf16_f32 v19, v22, v23
	v_cvt_pk_bf16_f32 v20, v38, v39
	v_cvt_pk_bf16_f32 v21, v40, v41
	global_store_dwordx4 v[28:29], v[24:27], off
	global_store_dwordx4 v[28:29], v[18:21], off offset:256
	s_and_saveexec_b64 s[28:29], s[6:7]
	s_cbranch_execz .LBB0_1105
	s_waitcnt lgkmcnt(0)
	v_add_f32_e32 v18, v16, v17
	v_lshlrev_b64 v[16:17], 6, v[90:91]
	v_lshl_add_u64 v[16:17], v[154:155], 0, v[16:17]
	v_lshl_add_u64 v[16:17], s[12:13], 2, v[16:17]
	s_lshl_b32 s20, s46, 2
	v_lshl_add_u64 v[16:17], v[16:17], 0, s[20:21]
	global_store_dword v[16:17], v18, off
